# RWKV pass-2 chunk carry moved from VALU+LDS matvec to f32 matrix cores (v_mfma_f32_16x16x4_f32, f32 operands and accumulation), P read straight from global in MFMA B layout
# speedup vs baseline: 1.0116x; 1.0116x over previous
.LBB0_938:
	s_and_b64 vcc, exec, s[4:5]
	s_cbranch_vccz .LBB0_945
	s_cmp_gt_u32 s63, 3
	s_cbranch_scc1 .Lcy0_idle
	s_lshr_b32 s2, s61, 3
	s_lshl_b32 s2, s2, 19
	s_and_b32 s3, s61, 7
	s_lshl_b32 s3, s3, 11
	s_and_b32 s10, s63, 3
	s_lshl_b32 s11, s10, 6
	s_add_u32 s4, s58, s2
	s_addc_u32 s5, s59, 0
	s_add_u32 s6, s64, s2
	s_addc_u32 s7, s65, 0
	s_add_u32 s12, s0, s2
	s_addc_u32 s13, s1, 0
	s_add_u32 s14, s3, s11
	v_and_b32_e32 v146, 15, v66
	v_lshrrev_b32_e32 v147, 4, v66
	v_lshlrev_b32_e32 v150, 12, v147
	v_lshl_add_u32 v150, v146, 2, v150
	v_add_u32_e32 v150, s11, v150
	v_lshlrev_b32_e32 v151, 10, v147
	v_lshl_add_u32 v151, v146, 2, v151
	v_add_u32_e32 v151, s14, v151
	v_mul_u32_u24_e32 v152, 0x440, v147
	v_lshl_add_u32 v152, v146, 2, v152
	v_add_u32_e32 v152, s11, v152
	v_and_b32_e32 v153, 7, v146
	v_mul_u32_u24_e32 v153, 0x110, v153
	v_lshl_add_u32 v153, v147, 6, v153
	v_mov_b32_e32 v228, 0
	s_mov_b32 s16, -1
	s_mov_b32 s17, 0
	v_mov_b32_e32 v212, 0
	v_mov_b32_e32 v213, 0
	v_mov_b32_e32 v214, 0
	v_mov_b32_e32 v215, 0
	global_load_dword v176, v150, s[4:5]
	global_load_dword v177, v150, s[4:5] offset:256
	global_load_dword v178, v150, s[4:5] offset:512
	global_load_dword v179, v150, s[4:5] offset:768
	global_load_dword v180, v150, s[4:5] offset:1024
	global_load_dword v181, v150, s[4:5] offset:1280
	global_load_dword v182, v150, s[4:5] offset:1536
	global_load_dword v183, v150, s[4:5] offset:1792
	global_load_dword v184, v150, s[4:5] offset:2048
	global_load_dword v185, v150, s[4:5] offset:2304
	global_load_dword v186, v150, s[4:5] offset:2560
	global_load_dword v187, v150, s[4:5] offset:2816
	global_load_dword v188, v150, s[4:5] offset:3072
	global_load_dword v189, v150, s[4:5] offset:3328
	global_load_dword v190, v150, s[4:5] offset:3584
	global_load_dword v191, v150, s[4:5] offset:3840
	s_mov_b64 exec, s[16:17]
	global_load_dword v212, v151, s[6:7]
	global_load_dword v213, v151, s[6:7] offset:256
	global_load_dword v214, v151, s[6:7] offset:512
	global_load_dword v215, v151, s[6:7] offset:768
	s_mov_b64 exec, -1
	s_mov_b64 exec, s[16:17]
	global_store_dword v151, v228, s[12:13]
	global_store_dword v151, v228, s[12:13] offset:256
	global_store_dword v151, v228, s[12:13] offset:512
	global_store_dword v151, v228, s[12:13] offset:768
	ds_write_b32 v152, v228
	ds_write_b32 v152, v228 offset:272
	ds_write_b32 v152, v228 offset:544
	ds_write_b32 v152, v228 offset:816
	s_mov_b64 exec, -1
	s_add_u32 s12, s12, 0x4000
	s_addc_u32 s13, s13, 0
	s_mov_b32 s10, 0
	s_mov_b32 s15, 0
	s_waitcnt lgkmcnt(0)
	s_barrier
.Lcy0_loop:
	s_cmp_lt_u32 s10, 30
	s_cbranch_scc0 .Lcy0_nopfa
	s_add_u32 s4, s4, 0x4000
	s_addc_u32 s5, s5, 0
	s_add_u32 s6, s6, 0x4000
	s_addc_u32 s7, s7, 0
	v_mov_b32_e32 v216, 0
	v_mov_b32_e32 v217, 0
	v_mov_b32_e32 v218, 0
	v_mov_b32_e32 v219, 0
	global_load_dword v192, v150, s[4:5]
	global_load_dword v193, v150, s[4:5] offset:256
	global_load_dword v194, v150, s[4:5] offset:512
	global_load_dword v195, v150, s[4:5] offset:768
	global_load_dword v196, v150, s[4:5] offset:1024
	global_load_dword v197, v150, s[4:5] offset:1280
	global_load_dword v198, v150, s[4:5] offset:1536
	global_load_dword v199, v150, s[4:5] offset:1792
	global_load_dword v200, v150, s[4:5] offset:2048
	global_load_dword v201, v150, s[4:5] offset:2304
	global_load_dword v202, v150, s[4:5] offset:2560
	global_load_dword v203, v150, s[4:5] offset:2816
	global_load_dword v204, v150, s[4:5] offset:3072
	global_load_dword v205, v150, s[4:5] offset:3328
	global_load_dword v206, v150, s[4:5] offset:3584
	global_load_dword v207, v150, s[4:5] offset:3840
	s_mov_b64 exec, s[16:17]
	global_load_dword v216, v151, s[6:7]
	global_load_dword v217, v151, s[6:7] offset:256
	global_load_dword v218, v151, s[6:7] offset:512
	global_load_dword v219, v151, s[6:7] offset:768
	s_mov_b64 exec, -1
	v_add_u32_e32 v154, s15, v153
	ds_read_b128 v[160:163], v154
	ds_read_b128 v[164:167], v154 offset:16
	ds_read_b128 v[168:171], v154 offset:32
	ds_read_b128 v[172:175], v154 offset:48
	s_waitcnt vmcnt(24)
	s_branch .Lcy0_goa
.Lcy0_nopfa:
	v_add_u32_e32 v154, s15, v153
	ds_read_b128 v[160:163], v154
	ds_read_b128 v[164:167], v154 offset:16
	ds_read_b128 v[168:171], v154 offset:32
	ds_read_b128 v[172:175], v154 offset:48
	s_waitcnt vmcnt(0)
.Lcy0_goa:
	v_mov_b32_e32 v220, v212
	v_mov_b32_e32 v221, v213
	v_mov_b32_e32 v222, v214
	v_mov_b32_e32 v223, v215
	v_mov_b32_e32 v224, 0
	v_mov_b32_e32 v225, 0
	v_mov_b32_e32 v226, 0
	v_mov_b32_e32 v227, 0
	s_nop 1
	s_waitcnt lgkmcnt(3)
	v_mfma_f32_16x16x4_f32 v[220:223], v160, v176, v[220:223]
	v_mfma_f32_16x16x4_f32 v[224:227], v161, v177, v[224:227]
	v_mfma_f32_16x16x4_f32 v[220:223], v162, v178, v[220:223]
	v_mfma_f32_16x16x4_f32 v[224:227], v163, v179, v[224:227]
	s_waitcnt lgkmcnt(2)
	v_mfma_f32_16x16x4_f32 v[220:223], v164, v180, v[220:223]
	v_mfma_f32_16x16x4_f32 v[224:227], v165, v181, v[224:227]
	v_mfma_f32_16x16x4_f32 v[220:223], v166, v182, v[220:223]
	v_mfma_f32_16x16x4_f32 v[224:227], v167, v183, v[224:227]
	s_waitcnt lgkmcnt(1)
	v_mfma_f32_16x16x4_f32 v[220:223], v168, v184, v[220:223]
	v_mfma_f32_16x16x4_f32 v[224:227], v169, v185, v[224:227]
	v_mfma_f32_16x16x4_f32 v[220:223], v170, v186, v[220:223]
	v_mfma_f32_16x16x4_f32 v[224:227], v171, v187, v[224:227]
	s_waitcnt lgkmcnt(0)
	v_mfma_f32_16x16x4_f32 v[220:223], v172, v188, v[220:223]
	v_mfma_f32_16x16x4_f32 v[224:227], v173, v189, v[224:227]
	v_mfma_f32_16x16x4_f32 v[220:223], v174, v190, v[220:223]
	v_mfma_f32_16x16x4_f32 v[224:227], v175, v191, v[224:227]
	s_xor_b32 s15, s15, 0x880
	v_add_u32_e32 v155, s15, v152
	s_add_u32 s10, s10, 1
	s_nop 9
	v_add_f32_e32 v220, v220, v224
	v_add_f32_e32 v221, v221, v225
	v_add_f32_e32 v222, v222, v226
	v_add_f32_e32 v223, v223, v227
	s_mov_b64 exec, s[16:17]
	ds_write_b32 v155, v220
	ds_write_b32 v155, v221 offset:272
	ds_write_b32 v155, v222 offset:544
	ds_write_b32 v155, v223 offset:816
	global_store_dword v151, v220, s[12:13]
	global_store_dword v151, v221, s[12:13] offset:256
	global_store_dword v151, v222, s[12:13] offset:512
	global_store_dword v151, v223, s[12:13] offset:768
	s_mov_b64 exec, -1
	s_add_u32 s12, s12, 0x4000
	s_addc_u32 s13, s13, 0
	s_waitcnt lgkmcnt(0)
	s_barrier
	s_cmp_gt_u32 s10, 30
	s_cbranch_scc1 .Lcy0_done
	s_cmp_lt_u32 s10, 30
	s_cbranch_scc0 .Lcy0_nopfb
	s_add_u32 s4, s4, 0x4000
	s_addc_u32 s5, s5, 0
	s_add_u32 s6, s6, 0x4000
	s_addc_u32 s7, s7, 0
	v_mov_b32_e32 v212, 0
	v_mov_b32_e32 v213, 0
	v_mov_b32_e32 v214, 0
	v_mov_b32_e32 v215, 0
	global_load_dword v176, v150, s[4:5]
	global_load_dword v177, v150, s[4:5] offset:256
	global_load_dword v178, v150, s[4:5] offset:512
	global_load_dword v179, v150, s[4:5] offset:768
	global_load_dword v180, v150, s[4:5] offset:1024
	global_load_dword v181, v150, s[4:5] offset:1280
	global_load_dword v182, v150, s[4:5] offset:1536
	global_load_dword v183, v150, s[4:5] offset:1792
	global_load_dword v184, v150, s[4:5] offset:2048
	global_load_dword v185, v150, s[4:5] offset:2304
	global_load_dword v186, v150, s[4:5] offset:2560
	global_load_dword v187, v150, s[4:5] offset:2816
	global_load_dword v188, v150, s[4:5] offset:3072
	global_load_dword v189, v150, s[4:5] offset:3328
	global_load_dword v190, v150, s[4:5] offset:3584
	global_load_dword v191, v150, s[4:5] offset:3840
	s_mov_b64 exec, s[16:17]
	global_load_dword v212, v151, s[6:7]
	global_load_dword v213, v151, s[6:7] offset:256
	global_load_dword v214, v151, s[6:7] offset:512
	global_load_dword v215, v151, s[6:7] offset:768
	s_mov_b64 exec, -1
	v_add_u32_e32 v154, s15, v153
	ds_read_b128 v[160:163], v154
	ds_read_b128 v[164:167], v154 offset:16
	ds_read_b128 v[168:171], v154 offset:32
	ds_read_b128 v[172:175], v154 offset:48
	s_waitcnt vmcnt(24)
	s_branch .Lcy0_gob

.Lcy0_gob:
	v_mov_b32_e32 v220, v216
	v_mov_b32_e32 v221, v217
	v_mov_b32_e32 v222, v218
	v_mov_b32_e32 v223, v219
	v_mov_b32_e32 v224, 0
	v_mov_b32_e32 v225, 0
	v_mov_b32_e32 v226, 0
	v_mov_b32_e32 v227, 0
	s_nop 1
	s_waitcnt lgkmcnt(3)
	v_mfma_f32_16x16x4_f32 v[220:223], v160, v192, v[220:223]
	v_mfma_f32_16x16x4_f32 v[224:227], v161, v193, v[224:227]
	v_mfma_f32_16x16x4_f32 v[220:223], v162, v194, v[220:223]
	v_mfma_f32_16x16x4_f32 v[224:227], v163, v195, v[224:227]
	s_waitcnt lgkmcnt(2)
	v_mfma_f32_16x16x4_f32 v[220:223], v164, v196, v[220:223]
	v_mfma_f32_16x16x4_f32 v[224:227], v165, v197, v[224:227]
	v_mfma_f32_16x16x4_f32 v[220:223], v166, v198, v[220:223]
	v_mfma_f32_16x16x4_f32 v[224:227], v167, v199, v[224:227]
	s_waitcnt lgkmcnt(1)
	v_mfma_f32_16x16x4_f32 v[220:223], v168, v200, v[220:223]
	v_mfma_f32_16x16x4_f32 v[224:227], v169, v201, v[224:227]
	v_mfma_f32_16x16x4_f32 v[220:223], v170, v202, v[220:223]
	v_mfma_f32_16x16x4_f32 v[224:227], v171, v203, v[224:227]
	s_waitcnt lgkmcnt(0)
	v_mfma_f32_16x16x4_f32 v[220:223], v172, v204, v[220:223]
	v_mfma_f32_16x16x4_f32 v[224:227], v173, v205, v[224:227]
	v_mfma_f32_16x16x4_f32 v[220:223], v174, v206, v[220:223]
	v_mfma_f32_16x16x4_f32 v[224:227], v175, v207, v[224:227]
	s_xor_b32 s15, s15, 0x880
	v_add_u32_e32 v155, s15, v152
	s_add_u32 s10, s10, 1
	s_nop 9
	v_add_f32_e32 v220, v220, v224
	v_add_f32_e32 v221, v221, v225
	v_add_f32_e32 v222, v222, v226
	v_add_f32_e32 v223, v223, v227
	s_mov_b64 exec, s[16:17]
	ds_write_b32 v155, v220
	ds_write_b32 v155, v221 offset:272
	ds_write_b32 v155, v222 offset:544
	ds_write_b32 v155, v223 offset:816
	global_store_dword v151, v220, s[12:13]
	global_store_dword v151, v221, s[12:13] offset:256
	global_store_dword v151, v222, s[12:13] offset:512
	global_store_dword v151, v223, s[12:13] offset:768
	s_mov_b64 exec, -1
	s_add_u32 s12, s12, 0x4000
	s_addc_u32 s13, s13, 0
	s_waitcnt lgkmcnt(0)
	s_barrier
	s_branch .Lcy0_loop
.Lcy0_idle:
	s_mov_b32 s10, 32
.Lcy0_idlel:
	s_barrier
	s_sub_u32 s10, s10, 1
	s_cmp_lg_u32 s10, 0
	s_cbranch_scc1 .Lcy0_idlel
.Lcy0_done:
.LBB0_945:
	s_waitcnt vmcnt(0)
	s_barrier
	s_and_saveexec_b64 s[4:5], s[86:87]
	s_cbranch_execz .LBB0_997
	s_add_i32 s2, 0, 0x23fc0
	v_mov_b32_e32 v0, s2
	s_waitcnt vmcnt(0) expcnt(0) lgkmcnt(0)
	ds_read_b32 v2, v0
	s_add_i32 s2, 0, 0x23fc4
	v_mov_b32_e32 v0, s2
	ds_read_b32 v0, v0
	s_waitcnt lgkmcnt(1)
	v_cmp_ne_u32_e32 vcc, 0, v2
	s_cbranch_vccnz .LBB0_961
	s_add_u32 s6, s40, 0x1000
	s_load_dwordx2 s[2:3], s[38:39], 0x4
	s_addc_u32 s7, s41, 0
	s_add_u32 s10, s40, 0x1100
	s_addc_u32 s11, s41, 0
	s_add_u32 s12, s40, 0x1200
	s_addc_u32 s13, s41, 0
	s_waitcnt lgkmcnt(0)
	s_mul_i32 s2, s2, s60
	s_add_u32 s14, s40, 0x1300
	s_mul_i32 s2, s2, s3
	s_addc_u32 s15, s41, 0
	s_mov_b32 s3, 1
	v_mov_b32_e32 v16, 0
	s_branch .LBB0_949
